# layer-1 rmsnorm rows: next row's residual loads prefetched one row ahead, gains loaded once
# baseline (speedup 1.0000x reference)
; #define GAS __attribute__((address_space(1)))
; __device__ __forceinline__ float bf_lo(unsigned u) { return __uint_as_float(u << 16); }
; __device__ __forceinline__ float bf_hi(unsigned u) { return __uint_as_float(u & 0xffff0000u); }
;     __device__ __forceinline__ GAS unsigned char* wsp() const { return (GAS unsigned char*)rd(18); }
; #define F_norm_g F.in(7)
; __device__ __forceinline__ void phase_xn_fused(Frame& F, int l) {
;     ...
;     const int gw = F.vcu * 8 + F.wave, NGW = F.G * 8;
;     GAS bf16* HB = (GAS bf16*)(F.wsp() + WS_H); GAS bf16* XN = (GAS bf16*)(F.wsp() + WS_XN); const GAS bf16* sl = (const GAS bf16*)(F.wsp() + WS_SLAB_O); const GAS float* gn = F_norm_g + (size_t)l * D;
;     for (int r = gw; r < MTOT; r += NGW) {
;         if (r >= MP && r < MPAD) { zero_xn_row(XN + (size_t)r * D, lane); continue; }
;         GAS v2u* xb = (GAS v2u*)(HB + (size_t)r * D) + lane; const int pm = r >> 8, rr = r & 255;
;         f32x4 v[4]; float s = 0.f;
; #pragma unroll
;         for (int j = 0; j < 4; ++j) { const int idx = tab[4 * pm + j]; const v2u t = xb[64 * j]; v[j] = (f32x4){bf_lo(t.x), bf_hi(t.x), bf_lo(t.y), bf_hi(t.y)};
.LBB0_109:
	s_or_b64 exec, exec, s[26:27]
	v_readlane_b32 s12, v241, 45
	v_mov_b32_e32 v0, s18
	s_waitcnt lgkmcnt(0)
	v_mov_b32_e32 v3, s12
	s_barrier
	ds_read_b64 v[0:1], v0
	s_waitcnt vmcnt(0)
	ds_read_b64 v[4:5], v3
	v_readlane_b32 s14, v243, 5
	v_readlane_b32 s15, v243, 6
	s_andn2_b64 vcc, exec, s[14:15]
	s_waitcnt lgkmcnt(1)
	v_readfirstlane_b32 s27, v1
	v_readfirstlane_b32 s26, v0
	s_waitcnt lgkmcnt(0)
	v_readfirstlane_b32 s12, v5
	v_readfirstlane_b32 s13, v4
	s_cbranch_vccnz .LBB0_124
	v_mbcnt_lo_u32_b32 v0, -1, v2
	v_mbcnt_hi_u32_b32 v4, -1, v0
	v_lshlrev_b32_e32 v0, 2, v4
	v_ashrrev_i32_e32 v5, 31, v4
	v_ashrrev_i32_e32 v1, 31, v0
	v_mov_b32_e32 v6, s13
	v_mov_b32_e32 v7, s12
	v_lshl_add_u64 v[0:1], v[0:1], 1, s[26:27]
	s_mov_b64 s[12:13], 0xfd80000
	v_lshlrev_b64 v[8:9], 3, v[4:5]
	v_lshl_add_u64 v[0:1], v[0:1], 0, s[12:13]
	v_lshl_add_u64 v[2:3], s[26:27], 0, v[8:9]
	s_mov_b64 s[12:13], 0x9000000
	v_lshl_add_u64 v[2:3], v[2:3], 0, s[12:13]
	v_lshl_add_u64 v[4:5], v[4:5], 4, v[6:7]
	s_mov_b64 s[12:13], 0x1000
	v_lshl_add_u64 v[4:5], v[4:5], 0, s[12:13]
	v_readlane_b32 s12, v241, 30
	s_add_u32 s12, s26, s12
	v_readlane_b32 s13, v241, 31
	s_addc_u32 s13, s27, s13
	v_readlane_b32 s26, v241, 24
	v_readlane_b32 s14, v241, 28
	v_lshl_add_u64 v[6:7], s[12:13], 0, v[8:9]
	v_readlane_b32 s27, v241, 25
	v_readlane_b32 s12, v241, 19
	s_mov_b32 s13, s14
	v_readlane_b32 s15, v241, 29
	v_add_co_u32_e32 v42, vcc, 0xfb700000, v6
	v_readlane_b32 s98, v241, 57
	v_addc_co_u32_e32 v43, vcc, -1, v7, vcc
	v_readlane_b32 s99, v241, 58
	global_load_dwordx2 v[44:45], v[42:43], off offset:-1024
	global_load_dwordx2 v[46:47], v[42:43], off offset:-512
	global_load_dwordx2 v[48:49], v[42:43], off
	global_load_dwordx2 v[50:51], v[42:43], off offset:512
	global_load_dwordx4 v[52:55], v[4:5], off
	global_load_dwordx4 v[56:59], v[4:5], off offset:1024
	global_load_dwordx4 v[60:63], v[4:5], off offset:2048
	global_load_dwordx4 v[64:67], v[4:5], off offset:3072
	s_branch .LBB0_112

; #define GAS __attribute__((address_space(1)))
; __device__ __forceinline__ unsigned cvt_pk_bf16(float lo, float hi) { const f32x2 v = {lo, hi}; return __builtin_bit_cast(unsigned, __builtin_convertvector(v, bf16n2)); }
; __device__ __forceinline__ float bf_lo(unsigned u) { return __uint_as_float(u << 16); }
; __device__ __forceinline__ float bf_hi(unsigned u) { return __uint_as_float(u & 0xffff0000u); }
; __device__ __forceinline__ void phase_xn_fused(Frame& F, int l) {
;     ...
;     for (int r = gw; r < MTOT; r += NGW) {
;         if (r >= MP && r < MPAD) { zero_xn_row(XN + (size_t)r * D, lane); continue; }
;         GAS v2u* xb = (GAS v2u*)(HB + (size_t)r * D) + lane; const int pm = r >> 8, rr = r & 255;
;         f32x4 v[4]; float s = 0.f;
; #pragma unroll
;         for (int j = 0; j < 4; ++j) { const int idx = tab[4 * pm + j]; const v2u t = xb[64 * j]; v[j] = (f32x4){bf_lo(t.x), bf_hi(t.x), bf_lo(t.y), bf_hi(t.y)};
;             if (idx >= 0) { v[j] += slab4_sum(sl + (size_t)(4 * idx) * 65536 + (size_t)rr * 256 + 4 * lane); v2u o; o.x = cvt_pk_bf16(v[j][0], v[j][1]); o.y = cvt_pk_bf16(v[j][2], v[j][3]); xb[64 * j] = o; }
.LBB0_112:
	s_waitcnt vmcnt(0)
	v_mov_b64_e32 v[80:81], v[44:45]
	v_mov_b64_e32 v[82:83], v[46:47]
	v_mov_b64_e32 v[84:85], v[48:49]
	v_mov_b64_e32 v[86:87], v[50:51]
	v_lshl_add_u64 v[42:43], v[42:43], 0, s[98:99]
	global_load_dwordx2 v[44:45], v[42:43], off offset:-1024
	global_load_dwordx2 v[46:47], v[42:43], off offset:-512
	global_load_dwordx2 v[48:49], v[42:43], off
	global_load_dwordx2 v[50:51], v[42:43], off offset:512
	s_and_b32 s14, s13, 0xffffff80
	s_cmpk_lg_i32 s14, 0x4080
	s_mov_b64 s[34:35], -1
	s_cbranch_scc0 .LBB0_122
	s_ashr_i32 s14, s13, 6
	s_lshl_b32 s14, s14, 2
	s_and_b32 s14, s14, -16
	s_add_i32 s14, s14, 0
	v_mov_b32_e32 v10, s14
	ds_read_b32 v12, v10
	s_and_b32 s15, s12, 0xff00
	s_lshl_b32 s20, s15, 1
	v_lshl_add_u64 v[20:21], v[0:1], 0, s[20:21]
	s_waitcnt lgkmcnt(0)
	v_cmp_gt_i32_e32 vcc, 0, v12
	s_and_b64 vcc, exec, vcc
	v_lshlrev_b32_e32 v10, 16, v80
	v_and_b32_e32 v11, 0xffff0000, v80
	v_lshlrev_b32_e32 v8, 16, v81
	v_and_b32_e32 v9, 0xffff0000, v81
	s_cbranch_vccnz .LBB0_115
	v_lshlrev_b32_e32 v172, 2, v12
	v_lshlrev_b64 v[12:13], 17, v[172:173]
	v_lshl_add_u64 v[12:13], v[20:21], 0, v[12:13]
	v_add_co_u32_e32 v16, vcc, 0x20000, v12
	global_load_dwordx2 v[14:15], v[12:13], off
	s_nop 0
	v_addc_co_u32_e32 v17, vcc, 0, v13, vcc
	v_add_co_u32_e32 v18, vcc, 0x40000, v12
	global_load_dwordx2 v[16:17], v[16:17], off
	s_nop 0
	v_addc_co_u32_e32 v19, vcc, 0, v13, vcc
	v_add_co_u32_e32 v12, vcc, 0x60000, v12
	global_load_dwordx2 v[18:19], v[18:19], off
	s_nop 0
	v_addc_co_u32_e32 v13, vcc, 0, v13, vcc
	global_load_dwordx2 v[12:13], v[12:13], off
	s_mov_b32 s16, 0xfb6ffc00
	s_mov_b32 s17, -1
	v_lshl_add_u64 v[22:23], v[6:7], 0, s[16:17]
	s_waitcnt vmcnt(3)
	v_lshlrev_b32_e32 v24, 16, v14
	v_and_b32_e32 v25, 0xffff0000, v14
	v_lshlrev_b32_e32 v14, 16, v15
	v_and_b32_e32 v15, 0xffff0000, v15
	s_waitcnt vmcnt(2)
	v_lshlrev_b32_e32 v26, 16, v16
	v_and_b32_e32 v27, 0xffff0000, v16
	v_lshlrev_b32_e32 v16, 16, v17
	v_and_b32_e32 v17, 0xffff0000, v17
	v_pk_add_f32 v[14:15], v[14:15], v[16:17]
	v_pk_add_f32 v[16:17], v[24:25], v[26:27]
	s_waitcnt vmcnt(1)
	v_lshlrev_b32_e32 v24, 16, v18
	v_and_b32_e32 v25, 0xffff0000, v18
	v_lshlrev_b32_e32 v18, 16, v19
	v_and_b32_e32 v19, 0xffff0000, v19
	s_waitcnt vmcnt(0)
	v_lshlrev_b32_e32 v26, 16, v12
	v_and_b32_e32 v27, 0xffff0000, v12
	v_lshlrev_b32_e32 v12, 16, v13
	v_and_b32_e32 v13, 0xffff0000, v13
	v_pk_add_f32 v[12:13], v[18:19], v[12:13]
	v_pk_add_f32 v[18:19], v[24:25], v[26:27]
	v_pk_add_f32 v[12:13], v[14:15], v[12:13]
	v_pk_add_f32 v[16:17], v[16:17], v[18:19]
	v_pk_add_f32 v[8:9], v[8:9], v[12:13]
	v_pk_add_f32 v[10:11], v[10:11], v[16:17]
	v_cvt_pk_bf16_f32 v13, v8, v9
	v_cvt_pk_bf16_f32 v12, v10, v11
	global_store_dwordx2 v[22:23], v[12:13], off
.LBB0_115:
	v_mov_b32_e32 v14, s14
	ds_read_b32 v16, v14 offset:4
	s_waitcnt lgkmcnt(0)
	v_cmp_gt_i32_e32 vcc, 0, v16
	s_and_b64 vcc, exec, vcc
	v_lshlrev_b32_e32 v14, 16, v82
	v_and_b32_e32 v15, 0xffff0000, v82
	v_lshlrev_b32_e32 v12, 16, v83
	v_and_b32_e32 v13, 0xffff0000, v83
	s_cbranch_vccnz .LBB0_117
	v_lshlrev_b32_e32 v172, 2, v16
	v_lshlrev_b64 v[16:17], 17, v[172:173]
	v_lshl_add_u64 v[16:17], v[20:21], 0, v[16:17]
	v_add_co_u32_e32 v22, vcc, 0x20000, v16
	global_load_dwordx2 v[18:19], v[16:17], off
	s_nop 0
	v_addc_co_u32_e32 v23, vcc, 0, v17, vcc
	v_add_co_u32_e32 v24, vcc, 0x40000, v16
	global_load_dwordx2 v[22:23], v[22:23], off
	s_nop 0
	v_addc_co_u32_e32 v25, vcc, 0, v17, vcc
	v_add_co_u32_e32 v16, vcc, 0x60000, v16
	global_load_dwordx2 v[24:25], v[24:25], off
	s_nop 0
	v_addc_co_u32_e32 v17, vcc, 0, v17, vcc
	global_load_dwordx2 v[16:17], v[16:17], off
	s_mov_b32 s16, 0xfb6ffe00
	s_mov_b32 s17, -1
	v_lshl_add_u64 v[26:27], v[6:7], 0, s[16:17]
	s_waitcnt vmcnt(3)
	v_lshlrev_b32_e32 v28, 16, v18
	v_and_b32_e32 v29, 0xffff0000, v18
	v_lshlrev_b32_e32 v18, 16, v19
	v_and_b32_e32 v19, 0xffff0000, v19
	s_waitcnt vmcnt(2)
	v_lshlrev_b32_e32 v30, 16, v22
	v_and_b32_e32 v31, 0xffff0000, v22
	v_lshlrev_b32_e32 v22, 16, v23
	v_and_b32_e32 v23, 0xffff0000, v23
	v_pk_add_f32 v[18:19], v[18:19], v[22:23]
	v_pk_add_f32 v[22:23], v[28:29], v[30:31]
	s_waitcnt vmcnt(1)
	v_lshlrev_b32_e32 v28, 16, v24
	v_and_b32_e32 v29, 0xffff0000, v24
	v_lshlrev_b32_e32 v24, 16, v25
	v_and_b32_e32 v25, 0xffff0000, v25
	s_waitcnt vmcnt(0)
	v_lshlrev_b32_e32 v30, 16, v16
	v_and_b32_e32 v31, 0xffff0000, v16
	v_lshlrev_b32_e32 v16, 16, v17
	v_and_b32_e32 v17, 0xffff0000, v17
	v_pk_add_f32 v[16:17], v[24:25], v[16:17]
	v_pk_add_f32 v[24:25], v[28:29], v[30:31]
	v_pk_add_f32 v[16:17], v[18:19], v[16:17]
	v_pk_add_f32 v[22:23], v[22:23], v[24:25]
	v_pk_add_f32 v[12:13], v[12:13], v[16:17]
	v_pk_add_f32 v[14:15], v[14:15], v[22:23]
	v_cvt_pk_bf16_f32 v17, v12, v13
	v_cvt_pk_bf16_f32 v16, v14, v15
	global_store_dwordx2 v[26:27], v[16:17], off
; __device__ __forceinline__ unsigned cvt_pk_bf16(float lo, float hi) { const f32x2 v = {lo, hi}; return __builtin_bit_cast(unsigned, __builtin_convertvector(v, bf16n2)); }
; __device__ __forceinline__ float bf_lo(unsigned u) { return __uint_as_float(u << 16); }
; __device__ __forceinline__ float bf_hi(unsigned u) { return __uint_as_float(u & 0xffff0000u); }
; __device__ __forceinline__ void phase_xn_fused(Frame& F, int l) {
;     ...
;         for (int j = 0; j < 4; ++j) { const int idx = tab[4 * pm + j]; const v2u t = xb[64 * j]; v[j] = (f32x4){bf_lo(t.x), bf_hi(t.x), bf_lo(t.y), bf_hi(t.y)};
;             if (idx >= 0) { v[j] += slab4_sum(sl + (size_t)(4 * idx) * 65536 + (size_t)rr * 256 + 4 * lane); v2u o; o.x = cvt_pk_bf16(v[j][0], v[j][1]); o.y = cvt_pk_bf16(v[j][2], v[j][3]); xb[64 * j] = o; }
.LBB0_117:
	v_mov_b32_e32 v18, s14
	ds_read_b32 v22, v18 offset:8
	s_waitcnt lgkmcnt(0)
	v_cmp_gt_i32_e32 vcc, 0, v22
	s_and_b64 vcc, exec, vcc
	v_lshlrev_b32_e32 v18, 16, v84
	v_and_b32_e32 v19, 0xffff0000, v84
	v_lshlrev_b32_e32 v16, 16, v85
	v_and_b32_e32 v17, 0xffff0000, v85
	s_cbranch_vccnz .LBB0_119
	v_lshlrev_b32_e32 v172, 2, v22
	v_lshlrev_b64 v[22:23], 17, v[172:173]
	v_lshl_add_u64 v[22:23], v[20:21], 0, v[22:23]
	v_add_co_u32_e32 v26, vcc, 0x20000, v22
	global_load_dwordx2 v[24:25], v[22:23], off
	s_nop 0
	v_addc_co_u32_e32 v27, vcc, 0, v23, vcc
	v_add_co_u32_e32 v28, vcc, 0x40000, v22
	global_load_dwordx2 v[26:27], v[26:27], off
	s_nop 0
	v_addc_co_u32_e32 v29, vcc, 0, v23, vcc
	v_add_co_u32_e32 v22, vcc, 0x60000, v22
	global_load_dwordx2 v[28:29], v[28:29], off
	s_nop 0
	v_addc_co_u32_e32 v23, vcc, 0, v23, vcc
	global_load_dwordx2 v[22:23], v[22:23], off
	s_mov_b32 s16, 0xfb700000
	s_mov_b32 s17, -1
	v_lshl_add_u64 v[30:31], v[6:7], 0, s[16:17]
	s_waitcnt vmcnt(3)
	v_lshlrev_b32_e32 v32, 16, v24
	v_and_b32_e32 v33, 0xffff0000, v24
	v_lshlrev_b32_e32 v24, 16, v25
	v_and_b32_e32 v25, 0xffff0000, v25
	s_waitcnt vmcnt(2)
	v_lshlrev_b32_e32 v34, 16, v26
	v_and_b32_e32 v35, 0xffff0000, v26
	v_lshlrev_b32_e32 v26, 16, v27
	v_and_b32_e32 v27, 0xffff0000, v27
	v_pk_add_f32 v[24:25], v[24:25], v[26:27]
	v_pk_add_f32 v[26:27], v[32:33], v[34:35]
	s_waitcnt vmcnt(1)
	v_lshlrev_b32_e32 v32, 16, v28
	v_and_b32_e32 v33, 0xffff0000, v28
	v_lshlrev_b32_e32 v28, 16, v29
	v_and_b32_e32 v29, 0xffff0000, v29
	s_waitcnt vmcnt(0)
	v_lshlrev_b32_e32 v34, 16, v22
	v_and_b32_e32 v35, 0xffff0000, v22
	v_lshlrev_b32_e32 v22, 16, v23
	v_and_b32_e32 v23, 0xffff0000, v23
	v_pk_add_f32 v[22:23], v[28:29], v[22:23]
	v_pk_add_f32 v[28:29], v[32:33], v[34:35]
	v_pk_add_f32 v[22:23], v[24:25], v[22:23]
	v_pk_add_f32 v[26:27], v[26:27], v[28:29]
	v_pk_add_f32 v[16:17], v[16:17], v[22:23]
	v_pk_add_f32 v[18:19], v[18:19], v[26:27]
	v_cvt_pk_bf16_f32 v23, v16, v17
	v_cvt_pk_bf16_f32 v22, v18, v19
	global_store_dwordx2 v[30:31], v[22:23], off
.LBB0_119:
	v_mov_b32_e32 v24, s14
	ds_read_b32 v26, v24 offset:12
	s_waitcnt lgkmcnt(0)
	v_cmp_gt_i32_e32 vcc, 0, v26
	s_and_b64 vcc, exec, vcc
	v_lshlrev_b32_e32 v24, 16, v86
	v_and_b32_e32 v25, 0xffff0000, v86
	v_lshlrev_b32_e32 v22, 16, v87
	v_and_b32_e32 v23, 0xffff0000, v87
	s_cbranch_vccnz .LBB0_121
	v_lshlrev_b32_e32 v172, 2, v26
	v_lshlrev_b64 v[26:27], 17, v[172:173]
	v_lshl_add_u64 v[20:21], v[20:21], 0, v[26:27]
	v_add_co_u32_e32 v28, vcc, 0x20000, v20
	global_load_dwordx2 v[26:27], v[20:21], off
	s_nop 0
	v_addc_co_u32_e32 v29, vcc, 0, v21, vcc
	v_add_co_u32_e32 v30, vcc, 0x40000, v20
	global_load_dwordx2 v[28:29], v[28:29], off
	s_nop 0
	v_addc_co_u32_e32 v31, vcc, 0, v21, vcc
	v_add_co_u32_e32 v20, vcc, 0x60000, v20
	global_load_dwordx2 v[30:31], v[30:31], off
	s_nop 0
	v_addc_co_u32_e32 v21, vcc, 0, v21, vcc
	global_load_dwordx2 v[20:21], v[20:21], off
	s_mov_b32 s14, 0xfb700200
	s_mov_b32 s15, -1
	v_lshl_add_u64 v[32:33], v[6:7], 0, s[14:15]
	s_waitcnt vmcnt(3)
	v_lshlrev_b32_e32 v34, 16, v26
	v_and_b32_e32 v35, 0xffff0000, v26
	v_lshlrev_b32_e32 v26, 16, v27
	v_and_b32_e32 v27, 0xffff0000, v27
	s_waitcnt vmcnt(2)
	v_lshlrev_b32_e32 v36, 16, v28
	v_and_b32_e32 v37, 0xffff0000, v28
	v_lshlrev_b32_e32 v28, 16, v29
	v_and_b32_e32 v29, 0xffff0000, v29
	v_pk_add_f32 v[26:27], v[26:27], v[28:29]
	v_pk_add_f32 v[28:29], v[34:35], v[36:37]
	s_waitcnt vmcnt(1)
	v_lshlrev_b32_e32 v34, 16, v30
	v_and_b32_e32 v35, 0xffff0000, v30
	v_lshlrev_b32_e32 v30, 16, v31
	v_and_b32_e32 v31, 0xffff0000, v31
	s_waitcnt vmcnt(0)
	v_lshlrev_b32_e32 v36, 16, v20
	v_and_b32_e32 v37, 0xffff0000, v20
	v_lshlrev_b32_e32 v20, 16, v21
	v_and_b32_e32 v21, 0xffff0000, v21
	v_pk_add_f32 v[20:21], v[30:31], v[20:21]
	v_pk_add_f32 v[30:31], v[34:35], v[36:37]
	v_pk_add_f32 v[20:21], v[26:27], v[20:21]
	v_pk_add_f32 v[28:29], v[28:29], v[30:31]
	v_pk_add_f32 v[22:23], v[22:23], v[20:21]
	v_pk_add_f32 v[24:25], v[24:25], v[28:29]
	v_cvt_pk_bf16_f32 v21, v22, v23
	v_cvt_pk_bf16_f32 v20, v24, v25
	global_store_dwordx2 v[32:33], v[20:21], off
; #define GAS __attribute__((address_space(1)))
; __device__ __forceinline__ unsigned cvt_pk_bf16(float lo, float hi) { const f32x2 v = {lo, hi}; return __builtin_bit_cast(unsigned, __builtin_convertvector(v, bf16n2)); }
; __device__ __forceinline__ float frsq(float x) { return __builtin_amdgcn_rsqf(x); }
; __device__ __forceinline__ void phase_xn_fused(Frame& F, int l) {
;     ...
;             s += (v[j].x * v[j].x + v[j].y * v[j].y) + (v[j].z * v[j].z + v[j].w * v[j].w); }
;         const float rs = frsq(wave_sum(s) * (1.f / D) + EPS);
;         GAS v2u* o8 = (GAS v2u*)(XN + (size_t)r * D) + lane;
; #pragma unroll
;         for (int j = 0; j < 4; ++j) { const f32x4 gg = ((const GAS f32x4*)gn)[lane + 64 * j]; v2u o; o.x = cvt_pk_bf16(v[j].x * rs * gg.x, v[j].y * rs * gg.y); o.y = cvt_pk_bf16(v[j].z * rs * gg.z, v[j].w * rs * gg.w); o8[64 * j] = o; }
.LBB0_121:
	v_mul_f32_e32 v34, v11, v11
	v_mul_f32_e32 v35, v9, v9
	v_mul_f32_e32 v36, v15, v15
	v_mul_f32_e32 v37, v13, v13
	v_and_b32_e32 v40, 64, v214
	v_mul_f32_e32 v38, v19, v19
	v_mul_f32_e32 v39, v17, v17
	v_pk_mul_f32 v[20:21], v[22:23], v[22:23]
	v_pk_mul_f32 v[30:31], v[24:25], v[24:25]
	v_xor_b32_e32 v41, 1, v214
	v_fmac_f32_e32 v34, v10, v10
	v_fmac_f32_e32 v35, v8, v8
	v_fmac_f32_e32 v36, v14, v14
	v_fmac_f32_e32 v37, v12, v12
	v_add_u32_e32 v40, 64, v40
	v_fmac_f32_e32 v38, v18, v18
	v_fmac_f32_e32 v39, v16, v16
	v_pk_mov_b32 v[32:33], v[30:31], v[20:21] op_sel:[1,0]
	v_mov_b32_e32 v31, v21
	v_add_f32_e32 v34, v34, v35
	v_add_f32_e32 v35, v36, v37
	v_cmp_lt_i32_e32 vcc, v41, v40
	v_add_f32_e32 v36, v38, v39
	v_pk_add_f32 v[20:21], v[32:33], v[30:31]
	v_cndmask_b32_e32 v30, v214, v41, vcc
	v_add_f32_e32 v31, v34, v35
	v_add_f32_e32 v20, v20, v21
	v_lshlrev_b32_e32 v21, 2, v30
	v_add_f32_e32 v30, v31, v36
	v_add_f32_e32 v20, v30, v20
	ds_bpermute_b32 v21, v21, v20
	v_xor_b32_e32 v30, 2, v214
	v_cmp_lt_i32_e32 vcc, v30, v40
	s_mov_b64 s[34:35], 0
	s_waitcnt lgkmcnt(0)
	v_add_f32_e32 v20, v20, v21
	v_cndmask_b32_e32 v30, v214, v30, vcc
	v_lshlrev_b32_e32 v30, 2, v30
	ds_bpermute_b32 v21, v30, v20
	v_xor_b32_e32 v30, 4, v214
	v_cmp_lt_i32_e32 vcc, v30, v40
	s_waitcnt lgkmcnt(0)
	v_add_f32_e32 v20, v20, v21
	v_cndmask_b32_e32 v30, v214, v30, vcc
	v_lshlrev_b32_e32 v30, 2, v30
	ds_bpermute_b32 v21, v30, v20
	v_xor_b32_e32 v30, 8, v214
	v_cmp_lt_i32_e32 vcc, v30, v40
	s_waitcnt lgkmcnt(0)
	v_add_f32_e32 v20, v20, v21
	v_cndmask_b32_e32 v30, v214, v30, vcc
	v_lshlrev_b32_e32 v30, 2, v30
	ds_bpermute_b32 v21, v30, v20
	v_xor_b32_e32 v30, 16, v214
	v_cmp_lt_i32_e32 vcc, v30, v40
	s_waitcnt lgkmcnt(0)
	v_add_f32_e32 v20, v20, v21
	v_cndmask_b32_e32 v30, v214, v30, vcc
	v_lshlrev_b32_e32 v30, 2, v30
	ds_bpermute_b32 v21, v30, v20
	v_xor_b32_e32 v30, 32, v214
	v_cmp_lt_i32_e32 vcc, v30, v40
	s_waitcnt lgkmcnt(0)
	v_add_f32_e32 v20, v20, v21
	v_cndmask_b32_e32 v30, v214, v30, vcc
	v_lshlrev_b32_e32 v30, 2, v30
	ds_bpermute_b32 v21, v30, v20
	s_waitcnt lgkmcnt(0)
	v_add_f32_e32 v20, v20, v21
	v_fmamk_f32 v20, v20, 0x3a800000, v212
	v_rsq_f32_e32 v20, v20
	s_nop 0
	v_pk_mul_f32 v[10:11], v[10:11], v[20:21] op_sel_hi:[1,0]
	v_pk_mul_f32 v[8:9], v[8:9], v[20:21] op_sel_hi:[1,0]
	v_pk_mul_f32 v[10:11], v[52:53], v[10:11]
	v_pk_mul_f32 v[8:9], v[54:55], v[8:9]
	v_cvt_pk_bf16_f32 v10, v10, v11
	v_cvt_pk_bf16_f32 v11, v8, v9
	global_store_dwordx2 v[6:7], v[10:11], off offset:-1024
	v_pk_mul_f32 v[14:15], v[14:15], v[20:21] op_sel_hi:[1,0]
	v_pk_mul_f32 v[12:13], v[12:13], v[20:21] op_sel_hi:[1,0]
	v_pk_mul_f32 v[8:9], v[56:57], v[14:15]
	v_pk_mul_f32 v[10:11], v[58:59], v[12:13]
	v_cvt_pk_bf16_f32 v8, v8, v9
	v_cvt_pk_bf16_f32 v9, v10, v11
	global_store_dwordx2 v[6:7], v[8:9], off offset:-512
	v_pk_mul_f32 v[12:13], v[18:19], v[20:21] op_sel_hi:[1,0]
	v_pk_mul_f32 v[14:15], v[16:17], v[20:21] op_sel_hi:[1,0]
	v_pk_mul_f32 v[8:9], v[60:61], v[12:13]
	v_pk_mul_f32 v[10:11], v[62:63], v[14:15]
	v_cvt_pk_bf16_f32 v8, v8, v9
	v_cvt_pk_bf16_f32 v9, v10, v11
	global_store_dwordx2 v[6:7], v[8:9], off
	v_pk_mul_f32 v[12:13], v[24:25], v[20:21] op_sel_hi:[1,0]
	v_pk_mul_f32 v[14:15], v[22:23], v[20:21] op_sel_hi:[1,0]
	v_pk_mul_f32 v[8:9], v[12:13], v[64:65]
	v_pk_mul_f32 v[10:11], v[14:15], v[66:67]
	v_cvt_pk_bf16_f32 v8, v8, v9
	v_cvt_pk_bf16_f32 v9, v10, v11

; __device__ __forceinline__ void phase_xn_fused(Frame& F, int l) {
;     ...
;     __syncthreads();
.LBB0_124:
	s_waitcnt vmcnt(0)
	s_barrier
